# attention diagonal-tile mask blocks: compare/select pairs share wait states (second compare into an SGPR pair) instead of s_nop padding each
# speedup vs baseline: 1.0086x; 1.0021x over previous
; #define MFMA(a, b, c) __builtin_amdgcn_mfma_f32_16x16x32_bf16((a), (b), (c), 0, 0, 0)
; template <int DK, bool BIAS> ...
;     ...
;     if (wact && 64 * j <= q0 + 32 * w + 31) {
;       f32x4 S[4][2];
; #pragma unroll
;       for (int kt = 0; kt < 4; ++kt)
; #pragma unroll
;         for (int qi = 0; qi < 2; ++qi) S[kt][qi] = (f32x4){0.f, 0.f, 0.f, 0.f};
; #pragma unroll
;       for (int ks = 0; ks < KS; ++ks)
; #pragma unroll
;         for (int kt = 0; kt < 4; ++kt) { const bf16x8 ak = *(const bf16x8*)(Ksm + (buf * 64 + 16 * kt + fr) * KST + 32 * ks + 8 * fq);
; #pragma unroll
;           for (int qi = 0; qi < 2; ++qi) S[kt][qi] = MFMA(ak, qf[qi][ks], S[kt][qi]); }
;       bf16x8 pf[2][2];
;       if (64 * j + 63 > q0 + 32 * w) {
; #pragma unroll
;         for (int qi = 0; qi < 2; ++qi) { const int qg = q0 + 32 * w + 16 * qi + fr;
; #pragma unroll
;           for (int kt = 0; kt < 4; ++kt)
; #pragma unroll
;             for (int r = 0; r < 4; ++r) { const int kg = 64 * j + 16 * kt + 4 * fq + r; if (kg > qg) S[kt][qi][r] = -1e30f; } }
;       }
.LBB0_1772:
	s_and_saveexec_b64 s[0:1], s[8:9]
	s_cbranch_execz .LBB0_1778
	v_cmp_le_i32_e32 vcc, s38, v167
	s_and_saveexec_b64 s[94:95], vcc
	s_cbranch_execz .LBB0_1777
	ds_read_b128 v[80:83], v169 offset:4608
	ds_read_b128 v[64:67], v169
	ds_read_b128 v[84:87], v169 offset:64
	ds_read_b128 v[72:75], v169 offset:2304
	s_add_i32 s18, s38, 63
	v_cmp_gt_i32_e32 vcc, s18, v127
	s_waitcnt lgkmcnt(3)
	v_mfma_f32_16x16x32_bf16 v[90:93], v[80:83], v[4:7], 0
	v_mfma_f32_16x16x32_bf16 v[94:97], v[80:83], v[12:15], 0
	ds_read_b128 v[80:83], v169 offset:6912
	s_waitcnt lgkmcnt(3)
	v_mfma_f32_16x16x32_bf16 v[68:71], v[64:67], v[4:7], 0
	s_waitcnt lgkmcnt(0)
	v_mfma_f32_16x16x32_bf16 v[116:119], v[80:83], v[4:7], 0
	v_mfma_f32_16x16x32_bf16 v[120:123], v[80:83], v[12:15], 0
	v_mfma_f32_16x16x32_bf16 v[80:83], v[84:87], v[0:3], v[68:71]
	s_nop 3
	ds_read_b128 v[68:71], v169 offset:2368
	v_mfma_f32_16x16x32_bf16 v[64:67], v[64:67], v[12:15], 0
	v_mfma_f32_16x16x32_bf16 v[76:79], v[72:75], v[4:7], 0
	v_mfma_f32_16x16x32_bf16 v[72:75], v[72:75], v[12:15], 0
	v_mfma_f32_16x16x32_bf16 v[64:67], v[84:87], v[8:11], v[64:67]
	s_waitcnt lgkmcnt(0)
	v_mfma_f32_16x16x32_bf16 v[86:89], v[68:71], v[0:3], v[76:79]
	v_mfma_f32_16x16x32_bf16 v[68:71], v[68:71], v[8:11], v[72:75]
	s_nop 2
	ds_read_b128 v[76:79], v169 offset:6976
	ds_read_b128 v[72:75], v169 offset:4672
	s_waitcnt lgkmcnt(0)
	v_mfma_f32_16x16x32_bf16 v[90:93], v[72:75], v[0:3], v[90:93]
	v_mfma_f32_16x16x32_bf16 v[72:75], v[72:75], v[8:11], v[94:97]
	v_mfma_f32_16x16x32_bf16 v[94:97], v[76:79], v[0:3], v[116:119]
	v_mfma_f32_16x16x32_bf16 v[76:79], v[76:79], v[8:11], v[120:123]
	s_and_saveexec_b64 s[18:19], vcc
	s_cbranch_execz .LBB0_1776
	v_add_u32_e32 v85, s38, v103
	v_mov_b32_e32 v84, s30
	v_cmp_gt_i32_e32 vcc, v85, v158
	v_add_u32_e32 v113, 2, v85
	v_add_u32_e32 v115, 3, v85
	v_cndmask_b32_e32 v84, v80, v84, vcc
	v_cmp_lt_i32_e32 vcc, v85, v158
	v_add_u32_e32 v116, 16, v85
	v_add_u32_e32 v117, 17, v85
	v_cndmask_b32_e32 v80, v84, v80, vcc
	v_cndmask_b32_e32 v81, v193, v81, vcc
	v_cmp_le_i32_e32 vcc, v113, v158
	v_mov_b32_e32 v84, s30
	v_add_u32_e32 v118, 18, v85
	v_cndmask_b32_e32 v82, v193, v82, vcc
	v_cmp_le_i32_e32 vcc, v115, v158
	v_add_u32_e32 v119, 19, v85
	v_add_u32_e32 v120, 32, v85
	v_cndmask_b32_e32 v83, v193, v83, vcc
	v_cmp_gt_i32_e32 vcc, v116, v158
	v_add_u32_e32 v121, 33, v85
	v_add_u32_e32 v122, 34, v85
	v_cndmask_b32_e32 v86, v86, v84, vcc
	v_cmp_le_i32_e32 vcc, v117, v158
	v_add_u32_e32 v123, 35, v85
	v_add_u32_e32 v124, 48, v85
	v_cndmask_b32_e32 v87, v193, v87, vcc
	v_cmp_le_i32_e32 vcc, v118, v158
	v_add_u32_e32 v125, 49, v85
	v_add_u32_e32 v126, 50, v85
	v_cndmask_b32_e32 v88, v193, v88, vcc
	v_cmp_le_i32_e32 vcc, v119, v158
	v_add_u32_e32 v131, 51, v85
	s_nop 0
	v_cndmask_b32_e32 v89, v193, v89, vcc
	v_cmp_gt_i32_e32 vcc, v120, v158
	v_cmp_le_i32_e64 s[100:101], v121, v158
	s_nop 0
	v_cndmask_b32_e32 v90, v90, v84, vcc
	v_cndmask_b32_e64 v91, v193, v91, s[100:101]
	v_cmp_le_i32_e32 vcc, v122, v158
	v_cmp_le_i32_e64 s[100:101], v123, v158
	s_nop 0
	v_cndmask_b32_e32 v92, v193, v92, vcc
	v_cndmask_b32_e64 v93, v193, v93, s[100:101]
	v_cmp_gt_i32_e32 vcc, v124, v158
	v_cmp_le_i32_e64 s[100:101], v125, v158
	s_nop 0
	v_cndmask_b32_e32 v94, v94, v84, vcc
	v_cndmask_b32_e64 v95, v193, v95, s[100:101]
	v_cmp_le_i32_e32 vcc, v126, v158
	v_cmp_le_i32_e64 s[100:101], v131, v158
	s_nop 0
	v_cndmask_b32_e32 v96, v193, v96, vcc
	v_cndmask_b32_e64 v97, v193, v97, s[100:101]
	v_cmp_gt_i32_e32 vcc, v85, v105
	s_nop 1
	v_cndmask_b32_e32 v84, v64, v84, vcc
	v_cmp_lt_i32_e32 vcc, v85, v105
	s_nop 1
	v_cndmask_b32_e32 v64, v84, v64, vcc
	v_cndmask_b32_e32 v65, v193, v65, vcc
	v_cmp_le_i32_e32 vcc, v113, v105
	v_mov_b32_e32 v84, s30
	s_nop 0
	v_cndmask_b32_e32 v66, v193, v66, vcc
	v_cmp_le_i32_e32 vcc, v115, v105
	v_cmp_gt_i32_e64 s[100:101], v116, v105
	s_nop 0
	v_cndmask_b32_e32 v67, v193, v67, vcc
	v_cndmask_b32_e64 v68, v68, v84, s[100:101]
	v_cmp_le_i32_e32 vcc, v117, v105
	v_cmp_le_i32_e64 s[100:101], v118, v105
	s_nop 0
	v_cndmask_b32_e32 v69, v193, v69, vcc
	v_cndmask_b32_e64 v70, v193, v70, s[100:101]
	v_cmp_le_i32_e32 vcc, v119, v105
	v_cmp_gt_i32_e64 s[100:101], v120, v105
	s_nop 0
	v_cndmask_b32_e32 v71, v193, v71, vcc
	v_cndmask_b32_e64 v72, v72, v84, s[100:101]
	v_cmp_le_i32_e32 vcc, v121, v105
	v_cmp_le_i32_e64 s[100:101], v122, v105
	s_nop 0
	v_cndmask_b32_e32 v73, v193, v73, vcc
	v_cndmask_b32_e64 v74, v193, v74, s[100:101]
	v_cmp_le_i32_e32 vcc, v123, v105
	v_cmp_gt_i32_e64 s[100:101], v124, v105
	s_nop 0
	v_cndmask_b32_e32 v75, v193, v75, vcc
	v_cndmask_b32_e64 v76, v76, v84, s[100:101]
	v_cmp_le_i32_e32 vcc, v125, v105
	v_cmp_le_i32_e64 s[100:101], v126, v105
	s_nop 0
	v_cndmask_b32_e32 v77, v193, v77, vcc
	v_cndmask_b32_e64 v78, v193, v78, s[100:101]
	v_cmp_le_i32_e32 vcc, v131, v105
	s_nop 1
	v_cndmask_b32_e32 v79, v193, v79, vcc

; #define MFMA(a, b, c) __builtin_amdgcn_mfma_f32_16x16x32_bf16((a), (b), (c), 0, 0, 0)
; template <int DK, bool BIAS> ...
;     ...
;     if (wact && 64 * j <= q0 + 32 * w + 31) {
;       f32x4 S[4][2];
; #pragma unroll
;       for (int kt = 0; kt < 4; ++kt)
; #pragma unroll
;         for (int qi = 0; qi < 2; ++qi) S[kt][qi] = (f32x4){0.f, 0.f, 0.f, 0.f};
; #pragma unroll
;       for (int ks = 0; ks < KS; ++ks)
; #pragma unroll
;         for (int kt = 0; kt < 4; ++kt) { const bf16x8 ak = *(const bf16x8*)(Ksm + (buf * 64 + 16 * kt + fr) * KST + 32 * ks + 8 * fq);
; #pragma unroll
;           for (int qi = 0; qi < 2; ++qi) S[kt][qi] = MFMA(ak, qf[qi][ks], S[kt][qi]); }
;       bf16x8 pf[2][2];
;       if (64 * j + 63 > q0 + 32 * w) {
; #pragma unroll
;         for (int qi = 0; qi < 2; ++qi) { const int qg = q0 + 32 * w + 16 * qi + fr;
; #pragma unroll
;           for (int kt = 0; kt < 4; ++kt)
; #pragma unroll
;             for (int r = 0; r < 4; ++r) { const int kg = 64 * j + 16 * kt + 4 * fq + r; if (kg > qg) S[kt][qi][r] = -1e30f; } }
;       }
.LBB0_1793:
	s_and_saveexec_b64 s[0:1], s[8:9]
	s_cbranch_execz .LBB0_1799
	s_add_i32 s18, s38, 64
	v_cmp_le_i32_e32 vcc, s18, v167
	s_and_saveexec_b64 s[92:93], vcc
	s_cbranch_execz .LBB0_1798
	ds_read_b128 v[80:83], v169 offset:13824
	ds_read_b128 v[64:67], v169 offset:9216
	ds_read_b128 v[84:87], v169 offset:9280
	ds_read_b128 v[72:75], v169 offset:11520
	s_add_i32 s18, s38, 0x7f
	v_cmp_gt_i32_e32 vcc, s18, v127
	s_waitcnt lgkmcnt(3)
	v_mfma_f32_16x16x32_bf16 v[90:93], v[80:83], v[4:7], 0
	v_mfma_f32_16x16x32_bf16 v[94:97], v[80:83], v[12:15], 0
	ds_read_b128 v[80:83], v169 offset:16128
	s_waitcnt lgkmcnt(3)
	v_mfma_f32_16x16x32_bf16 v[68:71], v[64:67], v[4:7], 0
	s_waitcnt lgkmcnt(0)
	v_mfma_f32_16x16x32_bf16 v[116:119], v[80:83], v[4:7], 0
	v_mfma_f32_16x16x32_bf16 v[120:123], v[80:83], v[12:15], 0
	v_mfma_f32_16x16x32_bf16 v[80:83], v[84:87], v[0:3], v[68:71]
	s_nop 3
	ds_read_b128 v[68:71], v169 offset:11584
	v_mfma_f32_16x16x32_bf16 v[64:67], v[64:67], v[12:15], 0
	v_mfma_f32_16x16x32_bf16 v[76:79], v[72:75], v[4:7], 0
	v_mfma_f32_16x16x32_bf16 v[72:75], v[72:75], v[12:15], 0
	v_mfma_f32_16x16x32_bf16 v[64:67], v[84:87], v[8:11], v[64:67]
	s_waitcnt lgkmcnt(0)
	v_mfma_f32_16x16x32_bf16 v[86:89], v[68:71], v[0:3], v[76:79]
	v_mfma_f32_16x16x32_bf16 v[68:71], v[68:71], v[8:11], v[72:75]
	s_nop 2
	ds_read_b128 v[76:79], v169 offset:16192
	ds_read_b128 v[72:75], v169 offset:13888
	s_waitcnt lgkmcnt(0)
	v_mfma_f32_16x16x32_bf16 v[90:93], v[72:75], v[0:3], v[90:93]
	v_mfma_f32_16x16x32_bf16 v[72:75], v[72:75], v[8:11], v[94:97]
	v_mfma_f32_16x16x32_bf16 v[94:97], v[76:79], v[0:3], v[116:119]
	v_mfma_f32_16x16x32_bf16 v[76:79], v[76:79], v[8:11], v[120:123]
	s_and_saveexec_b64 s[18:19], vcc
	s_cbranch_execz .LBB0_1797
	v_add_u32_e32 v85, s38, v103
	v_add_u32_e32 v113, 64, v85
	v_mov_b32_e32 v84, s30
	v_cmp_gt_i32_e32 vcc, v113, v158
	v_add_u32_e32 v115, 0x42, v85
	v_add_u32_e32 v116, 0x43, v85
	v_cndmask_b32_e32 v84, v80, v84, vcc
	v_cmp_lt_i32_e32 vcc, v113, v158
	v_add_u32_e32 v117, 0x50, v85
	v_add_u32_e32 v118, 0x51, v85
	v_cndmask_b32_e32 v80, v84, v80, vcc
	v_cndmask_b32_e32 v81, v193, v81, vcc
	v_cmp_le_i32_e32 vcc, v115, v158
	v_mov_b32_e32 v84, s30
	v_add_u32_e32 v119, 0x52, v85
	v_cndmask_b32_e32 v82, v193, v82, vcc
	v_cmp_le_i32_e32 vcc, v116, v158
	v_add_u32_e32 v120, 0x53, v85
	v_add_u32_e32 v121, 0x60, v85
	v_cndmask_b32_e32 v83, v193, v83, vcc
	v_cmp_gt_i32_e32 vcc, v117, v158
	v_add_u32_e32 v122, 0x61, v85
	v_add_u32_e32 v123, 0x62, v85
	v_cndmask_b32_e32 v86, v86, v84, vcc
	v_cmp_le_i32_e32 vcc, v118, v158
	v_add_u32_e32 v124, 0x63, v85
	v_add_u32_e32 v125, 0x70, v85
	v_cndmask_b32_e32 v87, v193, v87, vcc
	v_cmp_le_i32_e32 vcc, v119, v158
	v_add_u32_e32 v126, 0x71, v85
	v_add_u32_e32 v131, 0x72, v85
	v_cndmask_b32_e32 v88, v193, v88, vcc
	v_cmp_le_i32_e32 vcc, v120, v158
	v_add_u32_e32 v85, 0x73, v85
	s_nop 0
	v_cndmask_b32_e32 v89, v193, v89, vcc
	v_cmp_gt_i32_e32 vcc, v121, v158
	v_cmp_le_i32_e64 s[100:101], v122, v158
	s_nop 0
	v_cndmask_b32_e32 v90, v90, v84, vcc
	v_cndmask_b32_e64 v91, v193, v91, s[100:101]
	v_cmp_le_i32_e32 vcc, v123, v158
	v_cmp_le_i32_e64 s[100:101], v124, v158
	s_nop 0
	v_cndmask_b32_e32 v92, v193, v92, vcc
	v_cndmask_b32_e64 v93, v193, v93, s[100:101]
	v_cmp_gt_i32_e32 vcc, v125, v158
	v_cmp_le_i32_e64 s[100:101], v126, v158
	s_nop 0
	v_cndmask_b32_e32 v94, v94, v84, vcc
	v_cndmask_b32_e64 v95, v193, v95, s[100:101]
	v_cmp_le_i32_e32 vcc, v131, v158
	v_cmp_le_i32_e64 s[100:101], v85, v158
	s_nop 0
	v_cndmask_b32_e32 v96, v193, v96, vcc
	v_cndmask_b32_e64 v97, v193, v97, s[100:101]
	v_cmp_gt_i32_e32 vcc, v113, v105
	s_nop 1
	v_cndmask_b32_e32 v84, v64, v84, vcc
	v_cmp_lt_i32_e32 vcc, v113, v105
	s_nop 1
	v_cndmask_b32_e32 v64, v84, v64, vcc
	v_cndmask_b32_e32 v65, v193, v65, vcc
	v_cmp_le_i32_e32 vcc, v115, v105
	v_mov_b32_e32 v84, s30
	s_nop 0
	v_cndmask_b32_e32 v66, v193, v66, vcc
	v_cmp_le_i32_e32 vcc, v116, v105
	v_cmp_gt_i32_e64 s[100:101], v117, v105
	s_nop 0
	v_cndmask_b32_e32 v67, v193, v67, vcc
	v_cndmask_b32_e64 v68, v68, v84, s[100:101]
	v_cmp_le_i32_e32 vcc, v118, v105
	v_cmp_le_i32_e64 s[100:101], v119, v105
	s_nop 0
	v_cndmask_b32_e32 v69, v193, v69, vcc
	v_cndmask_b32_e64 v70, v193, v70, s[100:101]
	v_cmp_le_i32_e32 vcc, v120, v105
	v_cmp_gt_i32_e64 s[100:101], v121, v105
	s_nop 0
	v_cndmask_b32_e32 v71, v193, v71, vcc
	v_cndmask_b32_e64 v72, v72, v84, s[100:101]
	v_cmp_le_i32_e32 vcc, v122, v105
	v_cmp_le_i32_e64 s[100:101], v123, v105
	s_nop 0
	v_cndmask_b32_e32 v73, v193, v73, vcc
	v_cndmask_b32_e64 v74, v193, v74, s[100:101]
	v_cmp_le_i32_e32 vcc, v124, v105
	v_cmp_gt_i32_e64 s[100:101], v125, v105
	s_nop 0
	v_cndmask_b32_e32 v75, v193, v75, vcc
	v_cndmask_b32_e64 v76, v76, v84, s[100:101]
	v_cmp_le_i32_e32 vcc, v126, v105
	v_cmp_le_i32_e64 s[100:101], v131, v105
	s_nop 0
	v_cndmask_b32_e32 v77, v193, v77, vcc
	v_cndmask_b32_e64 v78, v193, v78, s[100:101]
	v_cmp_le_i32_e32 vcc, v85, v105
	s_nop 1
	v_cndmask_b32_e32 v79, v193, v79, vcc

; #define MFMA(a, b, c) __builtin_amdgcn_mfma_f32_16x16x32_bf16((a), (b), (c), 0, 0, 0)
; template <int DK, bool BIAS> ...
;     ...
;     if (wact && 64 * j <= q0 + 32 * w + 31) {
;       f32x4 S[4][2];
; #pragma unroll
;       for (int kt = 0; kt < 4; ++kt)
; #pragma unroll
;         for (int qi = 0; qi < 2; ++qi) S[kt][qi] = (f32x4){0.f, 0.f, 0.f, 0.f};
; #pragma unroll
;       for (int ks = 0; ks < KS; ++ks)
; #pragma unroll
;         for (int kt = 0; kt < 4; ++kt) { const bf16x8 ak = *(const bf16x8*)(Ksm + (buf * 64 + 16 * kt + fr) * KST + 32 * ks + 8 * fq);
; #pragma unroll
;           for (int qi = 0; qi < 2; ++qi) S[kt][qi] = MFMA(ak, qf[qi][ks], S[kt][qi]); }
;       bf16x8 pf[2][2];
;       if (64 * j + 63 > q0 + 32 * w) {
; #pragma unroll
;         for (int qi = 0; qi < 2; ++qi) { const int qg = q0 + 32 * w + 16 * qi + fr;
; #pragma unroll
;           for (int kt = 0; kt < 4; ++kt)
; #pragma unroll
;             for (int r = 0; r < 4; ++r) { const int kg = 64 * j + 16 * kt + 4 * fq + r; if (kg > qg) S[kt][qi][r] = -1e30f; } }
;       }
.LBB0_1862:
	s_and_saveexec_b64 s[0:1], s[8:9]
	s_cbranch_execz .LBB0_1868
	v_cmp_le_i32_e32 vcc, s58, v201
	s_and_saveexec_b64 s[94:95], vcc
	s_cbranch_execz .LBB0_1867
	ds_read_b128 v[80:83], v202
	ds_read_b128 v[156:159], v202 offset:64
	ds_read_b128 v[88:91], v202 offset:3328
	ds_read_b128 v[96:99], v202 offset:6656
	ds_read_b128 v[104:107], v202 offset:9984
	s_add_i32 s18, s58, 63
	v_cmp_gt_i32_e32 vcc, s18, v153
	s_waitcnt lgkmcnt(4)
	v_mfma_f32_16x16x32_bf16 v[84:87], v[80:83], v[4:7], 0
	v_mfma_f32_16x16x32_bf16 v[80:83], v[80:83], v[8:11], 0
	s_waitcnt lgkmcnt(3)
	v_mfma_f32_16x16x32_bf16 v[84:87], v[156:159], v[0:3], v[84:87]
	v_mfma_f32_16x16x32_bf16 v[80:83], v[156:159], v[20:23], v[80:83]
	ds_read_b128 v[156:159], v202 offset:3392
	s_waitcnt lgkmcnt(3)
	v_mfma_f32_16x16x32_bf16 v[92:95], v[88:91], v[4:7], 0
	v_mfma_f32_16x16x32_bf16 v[88:91], v[88:91], v[8:11], 0
	s_waitcnt lgkmcnt(0)
	v_mfma_f32_16x16x32_bf16 v[92:95], v[156:159], v[0:3], v[92:95]
	v_mfma_f32_16x16x32_bf16 v[156:159], v[156:159], v[20:23], v[88:91]
	s_nop 4
	ds_read_b128 v[88:91], v202 offset:6720
	v_mfma_f32_16x16x32_bf16 v[100:103], v[96:99], v[4:7], 0
	v_mfma_f32_16x16x32_bf16 v[96:99], v[96:99], v[8:11], 0
	s_waitcnt lgkmcnt(0)
	v_mfma_f32_16x16x32_bf16 v[160:163], v[88:91], v[0:3], v[100:103]
	v_mfma_f32_16x16x32_bf16 v[164:167], v[88:91], v[20:23], v[96:99]
	ds_read_b128 v[88:91], v202 offset:10048
	v_mfma_f32_16x16x32_bf16 v[108:111], v[104:107], v[4:7], 0
	v_mfma_f32_16x16x32_bf16 v[104:107], v[104:107], v[8:11], 0
	s_waitcnt lgkmcnt(0)
	v_mfma_f32_16x16x32_bf16 v[108:111], v[88:91], v[0:3], v[108:111]
	v_mfma_f32_16x16x32_bf16 v[168:171], v[88:91], v[20:23], v[104:107]
	ds_read_b128 v[88:91], v202 offset:128
	s_waitcnt lgkmcnt(0)
	v_mfma_f32_16x16x32_bf16 v[100:103], v[88:91], v[12:15], v[84:87]
	v_mfma_f32_16x16x32_bf16 v[88:91], v[88:91], v[16:19], v[80:83]
	s_nop 2
	ds_read_b128 v[80:83], v202 offset:3456
	s_waitcnt lgkmcnt(0)
	v_mfma_f32_16x16x32_bf16 v[96:99], v[80:83], v[12:15], v[92:95]
	s_nop 2
	ds_read_b128 v[92:95], v202 offset:10112
	v_mfma_f32_16x16x32_bf16 v[84:87], v[80:83], v[16:19], v[156:159]
	ds_read_b128 v[80:83], v202 offset:6784
	s_waitcnt lgkmcnt(0)
	v_mfma_f32_16x16x32_bf16 v[104:107], v[80:83], v[12:15], v[160:163]
	v_mfma_f32_16x16x32_bf16 v[80:83], v[80:83], v[16:19], v[164:167]
	v_mfma_f32_16x16x32_bf16 v[108:111], v[92:95], v[12:15], v[108:111]
	v_mfma_f32_16x16x32_bf16 v[92:95], v[92:95], v[16:19], v[168:171]
	s_and_saveexec_b64 s[18:19], vcc
	s_cbranch_execz .LBB0_1866
	v_add_u32_e32 v131, s58, v200
	v_mov_b32_e32 v156, s30
	v_cmp_gt_i32_e32 vcc, v131, v194
	v_add_u32_e32 v157, 3, v131
	v_add_u32_e32 v158, 16, v131
	v_cndmask_b32_e32 v155, v100, v156, vcc
	v_cmp_lt_i32_e32 vcc, v131, v194
	v_add_u32_e32 v159, 17, v131
	v_add_u32_e32 v160, 18, v131
	v_cndmask_b32_e32 v100, v155, v100, vcc
	v_add_u32_e32 v155, 2, v131
	v_cndmask_b32_e32 v101, v193, v101, vcc
	v_cmp_le_i32_e32 vcc, v155, v194
	v_add_u32_e32 v161, 19, v131
	v_add_u32_e32 v162, 32, v131
	v_cndmask_b32_e32 v102, v193, v102, vcc
	v_cmp_le_i32_e32 vcc, v157, v194
	v_add_u32_e32 v163, 33, v131
	v_add_u32_e32 v164, 34, v131
	v_cndmask_b32_e32 v103, v193, v103, vcc
	v_cmp_gt_i32_e32 vcc, v158, v194
	v_add_u32_e32 v165, 35, v131
	v_add_u32_e32 v166, 48, v131
	v_cndmask_b32_e32 v96, v96, v156, vcc
	v_cmp_le_i32_e32 vcc, v159, v194
	v_add_u32_e32 v167, 49, v131
	v_add_u32_e32 v168, 50, v131
	v_cndmask_b32_e32 v97, v193, v97, vcc
	v_cmp_le_i32_e32 vcc, v160, v194
	v_add_u32_e32 v169, 51, v131
	s_nop 0
	v_cndmask_b32_e32 v98, v193, v98, vcc
	v_cmp_le_i32_e32 vcc, v161, v194
	v_cmp_gt_i32_e64 s[100:101], v162, v194
	s_nop 0
	v_cndmask_b32_e32 v99, v193, v99, vcc
	v_cndmask_b32_e64 v104, v104, v156, s[100:101]
	v_cmp_le_i32_e32 vcc, v163, v194
	v_cmp_le_i32_e64 s[100:101], v164, v194
	s_nop 0
	v_cndmask_b32_e32 v105, v193, v105, vcc
	v_cndmask_b32_e64 v106, v193, v106, s[100:101]
	v_cmp_le_i32_e32 vcc, v165, v194
	v_cmp_gt_i32_e64 s[100:101], v166, v194
	s_nop 0
	v_cndmask_b32_e32 v107, v193, v107, vcc
	v_cndmask_b32_e64 v108, v108, v156, s[100:101]
	v_cmp_le_i32_e32 vcc, v167, v194
	v_cmp_le_i32_e64 s[100:101], v168, v194
	s_nop 0
	v_cndmask_b32_e32 v109, v193, v109, vcc
	v_cndmask_b32_e64 v110, v193, v110, s[100:101]
	v_cmp_le_i32_e32 vcc, v169, v194
	v_cmp_gt_i32_e64 s[100:101], v131, v195
	s_nop 0
	v_cndmask_b32_e32 v111, v193, v111, vcc
	v_cndmask_b32_e64 v156, v88, v156, s[100:101]
	v_cmp_lt_i32_e32 vcc, v131, v195
	s_nop 1
	v_cndmask_b32_e32 v88, v156, v88, vcc
	v_cndmask_b32_e32 v89, v193, v89, vcc
	v_cmp_le_i32_e32 vcc, v155, v195
	v_mov_b32_e32 v156, s30
	s_nop 0
	v_cndmask_b32_e32 v90, v193, v90, vcc
	v_cmp_le_i32_e32 vcc, v157, v195
	v_cmp_gt_i32_e64 s[100:101], v158, v195
	s_nop 0
	v_cndmask_b32_e32 v91, v193, v91, vcc
	v_cndmask_b32_e64 v84, v84, v156, s[100:101]
	v_cmp_le_i32_e32 vcc, v159, v195
	v_cmp_le_i32_e64 s[100:101], v160, v195
	s_nop 0
	v_cndmask_b32_e32 v85, v193, v85, vcc
	v_cndmask_b32_e64 v86, v193, v86, s[100:101]
	v_cmp_le_i32_e32 vcc, v161, v195
	v_cmp_gt_i32_e64 s[100:101], v162, v195
	s_nop 0
	v_cndmask_b32_e32 v87, v193, v87, vcc
	v_cndmask_b32_e64 v80, v80, v156, s[100:101]
	v_cmp_le_i32_e32 vcc, v163, v195
	v_cmp_le_i32_e64 s[100:101], v164, v195
	s_nop 0
	v_cndmask_b32_e32 v81, v193, v81, vcc
	v_cndmask_b32_e64 v82, v193, v82, s[100:101]
	v_cmp_le_i32_e32 vcc, v165, v195
	v_cmp_gt_i32_e64 s[100:101], v166, v195
	s_nop 0
	v_cndmask_b32_e32 v83, v193, v83, vcc
	v_cndmask_b32_e64 v92, v92, v156, s[100:101]
	v_cmp_le_i32_e32 vcc, v167, v195
	v_cmp_le_i32_e64 s[100:101], v168, v195
	s_nop 0
	v_cndmask_b32_e32 v93, v193, v93, vcc
	v_cndmask_b32_e64 v94, v193, v94, s[100:101]
	v_cmp_le_i32_e32 vcc, v169, v195
	s_nop 1
	v_cndmask_b32_e32 v95, v193, v95, vcc

; #define MFMA(a, b, c) __builtin_amdgcn_mfma_f32_16x16x32_bf16((a), (b), (c), 0, 0, 0)
; template <int DK, bool BIAS> ...
;     ...
;     if (wact && 64 * j <= q0 + 32 * w + 31) {
;       f32x4 S[4][2];
; #pragma unroll
;       for (int kt = 0; kt < 4; ++kt)
; #pragma unroll
;         for (int qi = 0; qi < 2; ++qi) S[kt][qi] = (f32x4){0.f, 0.f, 0.f, 0.f};
; #pragma unroll
;       for (int ks = 0; ks < KS; ++ks)
; #pragma unroll
;         for (int kt = 0; kt < 4; ++kt) { const bf16x8 ak = *(const bf16x8*)(Ksm + (buf * 64 + 16 * kt + fr) * KST + 32 * ks + 8 * fq);
; #pragma unroll
;           for (int qi = 0; qi < 2; ++qi) S[kt][qi] = MFMA(ak, qf[qi][ks], S[kt][qi]); }
;       bf16x8 pf[2][2];
;       if (64 * j + 63 > q0 + 32 * w) {
; #pragma unroll
;         for (int qi = 0; qi < 2; ++qi) { const int qg = q0 + 32 * w + 16 * qi + fr;
; #pragma unroll
;           for (int kt = 0; kt < 4; ++kt)
; #pragma unroll
;             for (int r = 0; r < 4; ++r) { const int kg = 64 * j + 16 * kt + 4 * fq + r; if (kg > qg) S[kt][qi][r] = -1e30f; } }
;       }
.LBB0_1885:
	s_add_i32 s16, s58, 64
	v_cmp_le_i32_e32 vcc, s16, v201
	s_and_saveexec_b64 s[16:17], vcc
	s_cbranch_execz .LBB0_1889
	ds_read_b128 v[80:83], v205
	ds_read_b128 v[156:159], v205 offset:64
	ds_read_b128 v[88:91], v205 offset:3328
	ds_read_b128 v[96:99], v205 offset:6656
	ds_read_b128 v[104:107], v205 offset:9984
	s_add_i32 s18, s58, 0x7f
	v_cmp_gt_i32_e32 vcc, s18, v153
	s_waitcnt lgkmcnt(4)
	v_mfma_f32_16x16x32_bf16 v[84:87], v[80:83], v[4:7], 0
	v_mfma_f32_16x16x32_bf16 v[80:83], v[80:83], v[8:11], 0
	s_waitcnt lgkmcnt(3)
	v_mfma_f32_16x16x32_bf16 v[84:87], v[156:159], v[0:3], v[84:87]
	v_mfma_f32_16x16x32_bf16 v[80:83], v[156:159], v[20:23], v[80:83]
	ds_read_b128 v[156:159], v205 offset:3392
	s_waitcnt lgkmcnt(3)
	v_mfma_f32_16x16x32_bf16 v[92:95], v[88:91], v[4:7], 0
	v_mfma_f32_16x16x32_bf16 v[88:91], v[88:91], v[8:11], 0
	s_waitcnt lgkmcnt(0)
	v_mfma_f32_16x16x32_bf16 v[92:95], v[156:159], v[0:3], v[92:95]
	v_mfma_f32_16x16x32_bf16 v[156:159], v[156:159], v[20:23], v[88:91]
	s_nop 4
	ds_read_b128 v[88:91], v205 offset:6720
	v_mfma_f32_16x16x32_bf16 v[100:103], v[96:99], v[4:7], 0
	v_mfma_f32_16x16x32_bf16 v[96:99], v[96:99], v[8:11], 0
	s_waitcnt lgkmcnt(0)
	v_mfma_f32_16x16x32_bf16 v[160:163], v[88:91], v[0:3], v[100:103]
	v_mfma_f32_16x16x32_bf16 v[164:167], v[88:91], v[20:23], v[96:99]
	ds_read_b128 v[88:91], v205 offset:10048
	v_mfma_f32_16x16x32_bf16 v[108:111], v[104:107], v[4:7], 0
	v_mfma_f32_16x16x32_bf16 v[104:107], v[104:107], v[8:11], 0
	s_waitcnt lgkmcnt(0)
	v_mfma_f32_16x16x32_bf16 v[108:111], v[88:91], v[0:3], v[108:111]
	v_mfma_f32_16x16x32_bf16 v[168:171], v[88:91], v[20:23], v[104:107]
	ds_read_b128 v[88:91], v205 offset:128
	s_waitcnt lgkmcnt(0)
	v_mfma_f32_16x16x32_bf16 v[100:103], v[88:91], v[12:15], v[84:87]
	s_nop 2
	ds_read_b128 v[84:87], v205 offset:6784
	v_mfma_f32_16x16x32_bf16 v[88:91], v[88:91], v[16:19], v[80:83]
	s_nop 2
	ds_read_b128 v[80:83], v205 offset:3456
	s_waitcnt lgkmcnt(0)
	v_mfma_f32_16x16x32_bf16 v[96:99], v[80:83], v[12:15], v[92:95]
	s_nop 2
	ds_read_b128 v[92:95], v205 offset:10112
	v_mfma_f32_16x16x32_bf16 v[80:83], v[80:83], v[16:19], v[156:159]
	v_mfma_f32_16x16x32_bf16 v[104:107], v[84:87], v[12:15], v[160:163]
	v_mfma_f32_16x16x32_bf16 v[84:87], v[84:87], v[16:19], v[164:167]
	s_waitcnt lgkmcnt(0)
	v_mfma_f32_16x16x32_bf16 v[108:111], v[92:95], v[12:15], v[108:111]
	v_mfma_f32_16x16x32_bf16 v[92:95], v[92:95], v[16:19], v[168:171]
	s_and_saveexec_b64 s[18:19], vcc
	s_cbranch_execz .LBB0_1888
	v_add_u32_e32 v131, s58, v200
	v_add_u32_e32 v155, 64, v131
	v_mov_b32_e32 v156, s30
	v_cmp_gt_i32_e32 vcc, v155, v194
	v_add_u32_e32 v157, 0x42, v131
	v_add_u32_e32 v158, 0x43, v131
	v_cndmask_b32_e32 v156, v100, v156, vcc
	v_cmp_lt_i32_e32 vcc, v155, v194
	v_add_u32_e32 v159, 0x50, v131
	v_add_u32_e32 v160, 0x51, v131
	v_cndmask_b32_e32 v100, v156, v100, vcc
	v_cndmask_b32_e32 v101, v193, v101, vcc
	v_cmp_le_i32_e32 vcc, v157, v194
	v_mov_b32_e32 v156, s30
	v_add_u32_e32 v161, 0x52, v131
	v_cndmask_b32_e32 v102, v193, v102, vcc
	v_cmp_le_i32_e32 vcc, v158, v194
	v_add_u32_e32 v162, 0x53, v131
	v_add_u32_e32 v163, 0x60, v131
	v_cndmask_b32_e32 v103, v193, v103, vcc
	v_cmp_gt_i32_e32 vcc, v159, v194
	v_add_u32_e32 v164, 0x61, v131
	v_add_u32_e32 v165, 0x62, v131
	v_cndmask_b32_e32 v96, v96, v156, vcc
	v_cmp_le_i32_e32 vcc, v160, v194
	v_add_u32_e32 v166, 0x63, v131
	v_add_u32_e32 v167, 0x70, v131
	v_cndmask_b32_e32 v97, v193, v97, vcc
	v_cmp_le_i32_e32 vcc, v161, v194
	v_add_u32_e32 v168, 0x71, v131
	v_add_u32_e32 v169, 0x72, v131
	v_cndmask_b32_e32 v98, v193, v98, vcc
	v_cmp_le_i32_e32 vcc, v162, v194
	v_add_u32_e32 v131, 0x73, v131
	s_nop 0
	v_cndmask_b32_e32 v99, v193, v99, vcc
	v_cmp_gt_i32_e32 vcc, v163, v194
	v_cmp_le_i32_e64 s[100:101], v164, v194
	s_nop 0
	v_cndmask_b32_e32 v104, v104, v156, vcc
	v_cndmask_b32_e64 v105, v193, v105, s[100:101]
	v_cmp_le_i32_e32 vcc, v165, v194
	v_cmp_le_i32_e64 s[100:101], v166, v194
	s_nop 0
	v_cndmask_b32_e32 v106, v193, v106, vcc
	v_cndmask_b32_e64 v107, v193, v107, s[100:101]
	v_cmp_gt_i32_e32 vcc, v167, v194
	v_cmp_le_i32_e64 s[100:101], v168, v194
	s_nop 0
	v_cndmask_b32_e32 v108, v108, v156, vcc
	v_cndmask_b32_e64 v109, v193, v109, s[100:101]
	v_cmp_le_i32_e32 vcc, v169, v194
	v_cmp_le_i32_e64 s[100:101], v131, v194
	s_nop 0
	v_cndmask_b32_e32 v110, v193, v110, vcc
	v_cndmask_b32_e64 v111, v193, v111, s[100:101]
	v_cmp_gt_i32_e32 vcc, v155, v195
	s_nop 1
	v_cndmask_b32_e32 v156, v88, v156, vcc
	v_cmp_lt_i32_e32 vcc, v155, v195
	s_nop 1
	v_cndmask_b32_e32 v88, v156, v88, vcc
	v_cndmask_b32_e32 v89, v193, v89, vcc
	v_cmp_le_i32_e32 vcc, v157, v195
	v_mov_b32_e32 v156, s30
	s_nop 0
	v_cndmask_b32_e32 v90, v193, v90, vcc
	v_cmp_le_i32_e32 vcc, v158, v195
	v_cmp_gt_i32_e64 s[100:101], v159, v195
	s_nop 0
	v_cndmask_b32_e32 v91, v193, v91, vcc
	v_cndmask_b32_e64 v80, v80, v156, s[100:101]
	v_cmp_le_i32_e32 vcc, v160, v195
	v_cmp_le_i32_e64 s[100:101], v161, v195
	s_nop 0
	v_cndmask_b32_e32 v81, v193, v81, vcc
	v_cndmask_b32_e64 v82, v193, v82, s[100:101]
	v_cmp_le_i32_e32 vcc, v162, v195
	v_cmp_gt_i32_e64 s[100:101], v163, v195
	s_nop 0
	v_cndmask_b32_e32 v83, v193, v83, vcc
	v_cndmask_b32_e64 v84, v84, v156, s[100:101]
	v_cmp_le_i32_e32 vcc, v164, v195
	v_cmp_le_i32_e64 s[100:101], v165, v195
	s_nop 0
	v_cndmask_b32_e32 v85, v193, v85, vcc
	v_cndmask_b32_e64 v86, v193, v86, s[100:101]
	v_cmp_le_i32_e32 vcc, v166, v195
	v_cmp_gt_i32_e64 s[100:101], v167, v195
	s_nop 0
	v_cndmask_b32_e32 v87, v193, v87, vcc
	v_cndmask_b32_e64 v92, v92, v156, s[100:101]
	v_cmp_le_i32_e32 vcc, v168, v195
	v_cmp_le_i32_e64 s[100:101], v169, v195
	s_nop 0
	v_cndmask_b32_e32 v93, v193, v93, vcc
	v_cndmask_b32_e64 v94, v193, v94, s[100:101]
	v_cmp_le_i32_e32 vcc, v131, v195
	s_nop 1
	v_cndmask_b32_e32 v95, v193, v95, vcc
